# v7 relaxed first-iteration waits plus pipelined LDS reads in SSD state-update MFMAs
# baseline (speedup 1.0000x reference)
; __device__ __forceinline__ unsigned pk2(float lo, float hi) { f32x2_t v = {lo, hi}; bf16x2_t b = __builtin_convertvector(v, bf16x2_t); return __builtin_bit_cast(unsigned, b); }
; __device__ __forceinline__ void ssd_phase(const Frame& F, const Args& a, int z, int li, bf16* PROJ, const float* DT, bf16* dryXB) {
;     ...
;                 if (hh == 0) { part[l31 * 8 + wave] = ss0; part[(32 + l31) * 8 + wave] = ss1; }
;                 __syncthreads();
;                 const f32x4 pa = *(const f32x4*)(part + l31 * 8), pb = *(const f32x4*)(part + l31 * 8 + 4), pc = *(const f32x4*)(part + (32 + l31) * 8), pd = *(const f32x4*)(part + (32 + l31) * 8 + 4);
;                 const float t0 = ((pa[0] + pa[1]) + (pa[2] + pa[3])) + ((pb[0] + pb[1]) + (pb[2] + pb[3])), t1 = ((pc[0] + pc[1]) + (pc[2] + pc[3])) + ((pd[0] + pd[1]) + (pd[2] + pd[3]));
;                 const float r0 = 1.0f / sqrtf(t0 * (1.f / 256.f) + RMS_EPS), r1 = 1.0f / sqrtf(t1 * (1.f / 256.f) + RMS_EPS);
;                 const float* nwp = norm_w + g * 256 + 64 * r + 32 * half + 4 * hh;
; #pragma unroll
;                 for (int i4 = 0; i4 < 4; ++i4) { const f32x4 nw = nwv[i4];
;                     u32x2 w0; w0.x = pk2(y0[4 * i4] * r0 * nw[0], y0[4 * i4 + 1] * r0 * nw[1]); w0.y = pk2(y0[4 * i4 + 2] * r0 * nw[2], y0[4 * i4 + 3] * r0 * nw[3]); if (!dryXB) *(u32x2*)(zr0 + 8 * i4) = w0; else if (g < 4) *(u32x2*)(dryXB + (rowc + l31) * 1024 + g * 256 + 64 * r + 32 * half + 4 * hh + 8 * i4) = w0;
;                     u32x2 w1; w1.x = pk2(y1[4 * i4] * r1 * nw[0], y1[4 * i4 + 1] * r1 * nw[1]); w1.y = pk2(y1[4 * i4 + 2] * r1 * nw[2], y1[4 * i4 + 3] * r1 * nw[3]); if (!dryXB) *(u32x2*)(zr1 + 8 * i4) = w1; else if (g < 4) *(u32x2*)(dryXB + (rowc + 32 + l31) * 1024 + g * 256 + 64 * r + 32 * half + 4 * hh + 8 * i4) = w1; }
.LBB0_407:
	s_or_b64 exec, exec, s[6:7]
	s_mov_b64 s[6:7], 0x60000
	v_lshl_add_u64 v[136:137], v[122:123], 0, s[6:7]
	s_mov_b64 s[6:7], 0x60010
	v_lshl_add_u64 v[138:139], v[122:123], 0, s[6:7]
	s_mov_b64 s[6:7], 0x60020
	s_waitcnt lgkmcnt(1)
	v_lshl_add_u64 v[116:117], v[122:123], 0, s[6:7]
	s_mov_b64 s[6:7], 0x60030
	s_waitcnt lgkmcnt(0)
	v_lshl_add_u64 v[114:115], v[122:123], 0, s[6:7]
	s_add_i32 s6, 0, 0x1fc00
	v_lshl_add_u32 v119, v144, 5, s6
	s_barrier
	ds_read_b128 v[124:127], v119
	ds_read_b128 v[128:131], v119 offset:16
	v_lshl_add_u32 v132, v118, 2, s6
	ds_read_b128 v[118:121], v132
	ds_read_b128 v[132:135], v132 offset:16
	s_add_i32 s50, s50, 64
	s_waitcnt lgkmcnt(3)
	v_mov_b32_e32 v140, v124
	s_waitcnt lgkmcnt(2)
	v_mov_b32_e32 v141, v128
	v_mov_b32_e32 v128, v125
	v_pk_add_f32 v[124:125], v[140:141], v[128:129]
	v_mov_b32_e32 v128, v126
	v_mov_b32_e32 v129, v130
	v_mov_b32_e32 v130, v127
	v_pk_add_f32 v[126:127], v[128:129], v[130:131]
	s_cmp_eq_u32 s35, s24
	v_pk_add_f32 v[124:125], v[124:125], v[126:127]
	s_nop 0
	v_add_f32_e32 v126, v124, v125
	s_waitcnt lgkmcnt(1)
	v_mov_b32_e32 v124, v118
	s_waitcnt lgkmcnt(0)
	v_mov_b32_e32 v125, v132
	v_mov_b32_e32 v132, v119
	v_pk_add_f32 v[118:119], v[124:125], v[132:133]
	v_mov_b32_e32 v124, v120
	v_mov_b32_e32 v125, v134
	v_mov_b32_e32 v134, v121
	v_pk_add_f32 v[120:121], v[124:125], v[134:135]
	s_nop 0
	v_pk_add_f32 v[118:119], v[118:119], v[120:121]
	s_nop 0
	v_add_f32_e32 v119, v118, v119
	v_fmamk_f32 v118, v126, 0x3b800000, v231
	v_cmp_gt_f32_e32 vcc, s41, v118
	v_mul_f32_e32 v120, 0x4f800000, v118
	v_fmamk_f32 v119, v119, 0x3b800000, v231
	v_cndmask_b32_e32 v118, v118, v120, vcc
	v_sqrt_f32_e32 v120, v118
	s_nop 0
	v_add_u32_e32 v121, -1, v120
	v_fma_f32 v124, -v121, v120, v118
	v_cmp_ge_f32_e64 s[6:7], 0, v124
	v_add_u32_e32 v124, 1, v120
	s_nop 0
	v_cndmask_b32_e64 v121, v120, v121, s[6:7]
	v_fma_f32 v120, -v124, v120, v118
	v_cmp_lt_f32_e64 s[6:7], 0, v120
	s_nop 1
	v_cndmask_b32_e64 v120, v121, v124, s[6:7]
	v_mul_f32_e32 v121, 0x37800000, v120
	v_cndmask_b32_e32 v120, v120, v121, vcc
	v_cmp_class_f32_e32 vcc, v118, v226
	s_nop 1
	v_cndmask_b32_e32 v118, v120, v118, vcc
	v_div_scale_f32 v120, s[6:7], v118, v118, 1.0
	v_rcp_f32_e32 v121, v120
	s_nop 0
	v_fma_f32 v124, -v120, v121, 1.0
	v_fmac_f32_e32 v121, v124, v121
	v_div_scale_f32 v124, vcc, 1.0, v118, 1.0
	v_mul_f32_e32 v125, v124, v121
	v_fma_f32 v126, -v120, v125, v124
	v_fmac_f32_e32 v125, v126, v121
	v_fma_f32 v120, -v120, v125, v124
	v_div_fmas_f32 v120, v120, v121, v125
	v_div_fixup_f32 v118, v120, v118, 1.0
	v_cmp_gt_f32_e32 vcc, s41, v119
	v_mul_f32_e32 v120, 0x4f800000, v119
	s_nop 0
	v_cndmask_b32_e32 v119, v119, v120, vcc
	v_sqrt_f32_e32 v120, v119
	s_nop 0
	v_add_u32_e32 v121, -1, v120
	v_fma_f32 v124, -v121, v120, v119
	v_cmp_ge_f32_e64 s[6:7], 0, v124
	v_add_u32_e32 v124, 1, v120
	s_nop 0
	v_cndmask_b32_e64 v121, v120, v121, s[6:7]
	v_fma_f32 v120, -v124, v120, v119
	v_cmp_lt_f32_e64 s[6:7], 0, v120
	s_nop 1
	v_cndmask_b32_e64 v120, v121, v124, s[6:7]
	v_mul_f32_e32 v121, 0x37800000, v120
	v_cndmask_b32_e32 v120, v120, v121, vcc
	v_cmp_class_f32_e32 vcc, v119, v226
	s_nop 1
	v_cndmask_b32_e32 v119, v120, v119, vcc
	v_div_scale_f32 v120, s[6:7], v119, v119, 1.0
	v_rcp_f32_e32 v121, v120
	v_pk_mul_f32 v[98:99], v[98:99], v[118:119] op_sel_hi:[1,0]
	v_pk_mul_f32 v[100:101], v[100:101], v[118:119] op_sel_hi:[1,0]
	s_waitcnt vmcnt(3)
	v_pk_mul_f32 v[98:99], v[78:79], v[98:99]
	v_fma_f32 v124, -v120, v121, 1.0
	v_fmac_f32_e32 v121, v124, v121
	v_div_scale_f32 v124, vcc, 1.0, v119, 1.0
	v_mul_f32_e32 v125, v124, v121
	v_fma_f32 v126, -v120, v125, v124
	v_fmac_f32_e32 v125, v126, v121
	v_fma_f32 v120, -v120, v125, v124
	v_div_fmas_f32 v120, v120, v121, v125
	v_div_fixup_f32 v120, v120, v119, 1.0
	v_pk_mul_f32 v[82:83], v[82:83], v[120:121] op_sel_hi:[1,0]
	v_pk_mul_f32 v[100:101], v[80:81], v[100:101]
	v_pk_mul_f32 v[78:79], v[78:79], v[82:83]
	v_pk_mul_f32 v[82:83], v[84:85], v[120:121] op_sel_hi:[1,0]
	v_cvt_pk_bf16_f32 v78, v78, v79
	v_pk_mul_f32 v[80:81], v[80:81], v[82:83]
	v_cvt_pk_bf16_f32 v98, v98, v99
	v_cvt_pk_bf16_f32 v79, v80, v81
	global_store_dwordx2 v[136:137], v[78:79], off
	v_pk_mul_f32 v[78:79], v[102:103], v[118:119] op_sel_hi:[1,0]
	v_pk_mul_f32 v[80:81], v[104:105], v[118:119] op_sel_hi:[1,0]
	s_waitcnt vmcnt(3)
	v_pk_mul_f32 v[78:79], v[74:75], v[78:79]
	v_pk_mul_f32 v[80:81], v[76:77], v[80:81]
	v_cvt_pk_bf16_f32 v78, v78, v79
	v_cvt_pk_bf16_f32 v79, v80, v81
	global_store_dwordx2 v[122:123], v[78:79], off offset:16
	v_pk_mul_f32 v[78:79], v[86:87], v[120:121] op_sel_hi:[1,0]
	v_cvt_pk_bf16_f32 v99, v100, v101
	v_pk_mul_f32 v[74:75], v[74:75], v[78:79]
	v_pk_mul_f32 v[78:79], v[88:89], v[120:121] op_sel_hi:[1,0]
	v_cvt_pk_bf16_f32 v74, v74, v75
	v_pk_mul_f32 v[76:77], v[76:77], v[78:79]
	global_store_dwordx2 v[122:123], v[98:99], off
	v_cvt_pk_bf16_f32 v75, v76, v77
	global_store_dwordx2 v[138:139], v[74:75], off
	v_pk_mul_f32 v[74:75], v[106:107], v[118:119] op_sel_hi:[1,0]
	v_pk_mul_f32 v[76:77], v[108:109], v[118:119] op_sel_hi:[1,0]
	s_waitcnt vmcnt(5)
	v_pk_mul_f32 v[74:75], v[70:71], v[74:75]
	v_pk_mul_f32 v[76:77], v[72:73], v[76:77]
	v_cvt_pk_bf16_f32 v74, v74, v75
	v_cvt_pk_bf16_f32 v75, v76, v77
	global_store_dwordx2 v[122:123], v[74:75], off offset:32
	v_pk_mul_f32 v[74:75], v[90:91], v[120:121] op_sel_hi:[1,0]
	s_nop 0
	v_pk_mul_f32 v[70:71], v[70:71], v[74:75]
	v_pk_mul_f32 v[74:75], v[92:93], v[120:121] op_sel_hi:[1,0]
	v_cvt_pk_bf16_f32 v70, v70, v71
	v_pk_mul_f32 v[72:73], v[72:73], v[74:75]
	s_nop 0
	v_cvt_pk_bf16_f32 v71, v72, v73
	global_store_dwordx2 v[116:117], v[70:71], off
	v_pk_mul_f32 v[70:71], v[110:111], v[118:119] op_sel_hi:[1,0]
	v_pk_mul_f32 v[72:73], v[112:113], v[118:119] op_sel_hi:[1,0]
	s_waitcnt vmcnt(6)
; __device__ __forceinline__ unsigned pk2(float lo, float hi) { f32x2_t v = {lo, hi}; bf16x2_t b = __builtin_convertvector(v, bf16x2_t); return __builtin_bit_cast(unsigned, b); }
; __device__ __forceinline__ float fexp2(float x) { return __builtin_amdgcn_exp2f(x); }
; #define MFMA32(a, b, c) __builtin_amdgcn_mfma_f32_32x32x16_bf16((a), (b), (c), 0, 0, 0)
; __device__ __forceinline__ void ssd_phase(const Frame& F, const Args& a, int z, int li, bf16* PROJ, const float* DT, bf16* dryXB) {
;     ...
;                 for (int i4 = 0; i4 < 4; ++i4) { const f32x4 nw = nwv[i4];
;                     u32x2 w0; w0.x = pk2(y0[4 * i4] * r0 * nw[0], y0[4 * i4 + 1] * r0 * nw[1]); w0.y = pk2(y0[4 * i4 + 2] * r0 * nw[2], y0[4 * i4 + 3] * r0 * nw[3]); if (!dryXB) *(u32x2*)(zr0 + 8 * i4) = w0; else if (g < 4) *(u32x2*)(dryXB + (rowc + l31) * 1024 + g * 256 + 64 * r + 32 * half + 4 * hh + 8 * i4) = w0;
;                     u32x2 w1; w1.x = pk2(y1[4 * i4] * r1 * nw[0], y1[4 * i4 + 1] * r1 * nw[1]); w1.y = pk2(y1[4 * i4 + 2] * r1 * nw[2], y1[4 * i4 + 3] * r1 * nw[3]); if (!dryXB) *(u32x2*)(zr1 + 8 * i4) = w1; else if (g < 4) *(u32x2*)(dryXB + (rowc + 32 + l31) * 1024 + g * 256 + 64 * r + 32 * half + 4 * hh + 8 * i4) = w1; }
;             }
;             { const float dec = fexp2(cumr[63]);
; #pragma unroll
;               for (int nb = 0; nb < 4; ++nb)
; #pragma unroll
;                   for (int i = 0; i < 16; ++i) hT[nb][i] *= dec;
;               const bf16* xw = Xwt + (64 * r + 32 * half + l31) * 72; const int swx = 8 * ((4 * half + (l31 >> 3)) & 7), swn = 8 * (l31 >> 3);
; #pragma unroll
;               for (int ss = 0; ss < 4; ++ss) { const bf16x8 bx = *(const bf16x8*)(xw + ((16 * ss + 8 * hh) ^ swx));
; #pragma unroll
;                   for (int nb = 0; nb < 4; ++nb) { const bf16x8 af = *(const bf16x8*)(Bt + (32 * nb + l31) * 72 + ((16 * ss + 8 * hh) ^ swn ^ (32 * (nb & 1)))); hT[nb] = MFMA32(af, bx, hT[nb]); } }
;             }
;             __syncthreads();
	v_pk_mul_f32 v[70:71], v[66:67], v[70:71]
	v_pk_mul_f32 v[72:73], v[68:69], v[72:73]
	v_cvt_pk_bf16_f32 v70, v70, v71
	v_cvt_pk_bf16_f32 v71, v72, v73
	global_store_dwordx2 v[122:123], v[70:71], off offset:48
	v_pk_mul_f32 v[70:71], v[94:95], v[120:121] op_sel_hi:[1,0]
	s_nop 0
	v_pk_mul_f32 v[66:67], v[66:67], v[70:71]
	v_pk_mul_f32 v[70:71], v[96:97], v[120:121] op_sel_hi:[1,0]
	v_cvt_pk_bf16_f32 v66, v66, v67
	v_pk_mul_f32 v[68:69], v[68:69], v[70:71]
	v_xor_b32_e32 v71, v0, v142
	v_cvt_pk_bf16_f32 v67, v68, v69
	global_store_dwordx2 v[114:115], v[66:67], off
	v_mov_b32_e32 v66, s60
	ds_read_b32 v66, v66 offset:252
	s_waitcnt lgkmcnt(0)
	v_exp_f32_e32 v66, v66
	s_nop 0
	v_pk_mul_f32 v[64:65], v[64:65], v[66:67] op_sel_hi:[1,0]
	v_pk_mul_f32 v[62:63], v[62:63], v[66:67] op_sel_hi:[1,0]
	v_pk_mul_f32 v[60:61], v[60:61], v[66:67] op_sel_hi:[1,0]
	v_pk_mul_f32 v[58:59], v[58:59], v[66:67] op_sel_hi:[1,0]
	v_pk_mul_f32 v[56:57], v[56:57], v[66:67] op_sel_hi:[1,0]
	v_pk_mul_f32 v[54:55], v[54:55], v[66:67] op_sel_hi:[1,0]
	v_pk_mul_f32 v[52:53], v[52:53], v[66:67] op_sel_hi:[1,0]
	v_pk_mul_f32 v[50:51], v[50:51], v[66:67] op_sel_hi:[1,0]
	v_pk_mul_f32 v[48:49], v[48:49], v[66:67] op_sel_hi:[1,0]
	v_pk_mul_f32 v[46:47], v[46:47], v[66:67] op_sel_hi:[1,0]
	v_pk_mul_f32 v[44:45], v[44:45], v[66:67] op_sel_hi:[1,0]
	v_pk_mul_f32 v[42:43], v[42:43], v[66:67] op_sel_hi:[1,0]
	v_pk_mul_f32 v[40:41], v[40:41], v[66:67] op_sel_hi:[1,0]
	v_pk_mul_f32 v[38:39], v[38:39], v[66:67] op_sel_hi:[1,0]
	v_pk_mul_f32 v[36:37], v[36:37], v[66:67] op_sel_hi:[1,0]
	v_pk_mul_f32 v[34:35], v[34:35], v[66:67] op_sel_hi:[1,0]
	v_pk_mul_f32 v[32:33], v[32:33], v[66:67] op_sel_hi:[1,0]
	v_pk_mul_f32 v[30:31], v[30:31], v[66:67] op_sel_hi:[1,0]
	v_pk_mul_f32 v[28:29], v[28:29], v[66:67] op_sel_hi:[1,0]
	v_pk_mul_f32 v[26:27], v[26:27], v[66:67] op_sel_hi:[1,0]
	v_pk_mul_f32 v[24:25], v[24:25], v[66:67] op_sel_hi:[1,0]
	v_pk_mul_f32 v[22:23], v[22:23], v[66:67] op_sel_hi:[1,0]
	v_pk_mul_f32 v[20:21], v[20:21], v[66:67] op_sel_hi:[1,0]
	v_pk_mul_f32 v[18:19], v[18:19], v[66:67] op_sel_hi:[1,0]
	v_pk_mul_f32 v[16:17], v[16:17], v[66:67] op_sel_hi:[1,0]
	v_pk_mul_f32 v[14:15], v[14:15], v[66:67] op_sel_hi:[1,0]
	v_pk_mul_f32 v[12:13], v[12:13], v[66:67] op_sel_hi:[1,0]
	v_pk_mul_f32 v[10:11], v[10:11], v[66:67] op_sel_hi:[1,0]
	v_pk_mul_f32 v[8:9], v[8:9], v[66:67] op_sel_hi:[1,0]
	v_pk_mul_f32 v[6:7], v[6:7], v[66:67] op_sel_hi:[1,0]
	v_pk_mul_f32 v[4:5], v[4:5], v[66:67] op_sel_hi:[1,0]
	v_pk_mul_f32 v[2:3], v[2:3], v[66:67] op_sel_hi:[1,0]
	v_mov_b32_e32 v66, s44
	v_mad_u32_u24 v70, v144, s46, v66
	v_xor_b32_e32 v224, v0, v146
	v_xor_b32_e32 v225, v0, v142
	v_or_b32_e32 v71, 32, v142
	v_xor_b32_e32 v71, v0, v71
	v_lshl_add_u32 v77, v225, 1, v70
	v_lshl_add_u32 v76, v71, 1, v70
	v_lshl_add_u32 v0, v224, 1, v143
	ds_read_b128 v[66:69], v0 offset:36864
	ds_read_b128 v[72:75], v77
	ds_read_b128 v[234:237], v76 offset:4608
	ds_read_b128 v[240:243], v77 offset:9216
	ds_read_b128 v[244:247], v76 offset:13824
	v_xor_b32_e32 v0, 16, v224
	v_lshl_add_u32 v0, v0, 1, v143
	ds_read_b128 v[248:251], v0 offset:36864
	v_xor_b32_e32 v77, 16, v225
	v_xor_b32_e32 v76, 16, v71
	v_lshl_add_u32 v77, v77, 1, v70
	v_lshl_add_u32 v76, v76, 1, v70
	s_waitcnt lgkmcnt(4)
	v_mfma_f32_32x32x16_bf16 v[50:65], v[72:75], v[66:69], v[50:65]
	ds_read_b128 v[72:75], v77
	s_waitcnt lgkmcnt(4)
	v_mfma_f32_32x32x16_bf16 v[34:49], v[234:237], v[66:69], v[34:49]
	ds_read_b128 v[234:237], v76 offset:4608
	s_waitcnt lgkmcnt(4)
	v_mfma_f32_32x32x16_bf16 v[18:33], v[240:243], v[66:69], v[18:33]
	ds_read_b128 v[240:243], v77 offset:9216
	s_waitcnt lgkmcnt(4)
	v_mfma_f32_32x32x16_bf16 v[2:17], v[244:247], v[66:69], v[2:17]
	ds_read_b128 v[244:247], v76 offset:13824
	v_xor_b32_e32 v0, 32, v224
	v_lshl_add_u32 v0, v0, 1, v143
	ds_read_b128 v[66:69], v0 offset:36864
	v_xor_b32_e32 v77, 32, v225
	v_xor_b32_e32 v76, 32, v71
	v_lshl_add_u32 v77, v77, 1, v70
	v_lshl_add_u32 v76, v76, 1, v70
	s_waitcnt lgkmcnt(4)
	v_mfma_f32_32x32x16_bf16 v[50:65], v[72:75], v[248:251], v[50:65]
	ds_read_b128 v[72:75], v77
	s_waitcnt lgkmcnt(4)
	v_mfma_f32_32x32x16_bf16 v[34:49], v[234:237], v[248:251], v[34:49]
	ds_read_b128 v[234:237], v76 offset:4608
	s_waitcnt lgkmcnt(4)
	v_mfma_f32_32x32x16_bf16 v[18:33], v[240:243], v[248:251], v[18:33]
	ds_read_b128 v[240:243], v77 offset:9216
	s_waitcnt lgkmcnt(4)
	v_mfma_f32_32x32x16_bf16 v[2:17], v[244:247], v[248:251], v[2:17]
	ds_read_b128 v[244:247], v76 offset:13824
	v_xor_b32_e32 v0, 48, v224
	v_lshl_add_u32 v0, v0, 1, v143
	ds_read_b128 v[248:251], v0 offset:36864
	v_xor_b32_e32 v77, 48, v225
	v_xor_b32_e32 v76, 48, v71
	v_lshl_add_u32 v77, v77, 1, v70
	v_lshl_add_u32 v76, v76, 1, v70
	s_waitcnt lgkmcnt(4)
	v_mfma_f32_32x32x16_bf16 v[50:65], v[72:75], v[66:69], v[50:65]
	ds_read_b128 v[72:75], v77
	s_waitcnt lgkmcnt(4)
	v_mfma_f32_32x32x16_bf16 v[34:49], v[234:237], v[66:69], v[34:49]
	ds_read_b128 v[234:237], v76 offset:4608
	s_waitcnt lgkmcnt(4)
	v_mfma_f32_32x32x16_bf16 v[18:33], v[240:243], v[66:69], v[18:33]
	ds_read_b128 v[240:243], v77 offset:9216
	s_waitcnt lgkmcnt(4)
	v_mfma_f32_32x32x16_bf16 v[2:17], v[244:247], v[66:69], v[2:17]
	ds_read_b128 v[244:247], v76 offset:13824
	s_waitcnt lgkmcnt(3)
	v_mfma_f32_32x32x16_bf16 v[50:65], v[72:75], v[248:251], v[50:65]
	s_waitcnt lgkmcnt(2)
	v_mfma_f32_32x32x16_bf16 v[34:49], v[234:237], v[248:251], v[34:49]
	s_waitcnt lgkmcnt(1)
	v_mfma_f32_32x32x16_bf16 v[18:33], v[240:243], v[248:251], v[18:33]
	s_waitcnt lgkmcnt(0)
	s_barrier
	v_mfma_f32_32x32x16_bf16 v[2:17], v[244:247], v[248:251], v[2:17]
	s_cbranch_scc1 .LBB0_398
